# XCD-local grid barriers at 5 XCD-private seams (no L2 writeback/top hop), guarded by run-time blockIdx%8->XCC placement check; plus MLA loop edits
# speedup vs baseline: 1.0300x; 1.0116x over previous
; #define LAS __attribute__((address_space(3)))
; DI unsigned xb_add(unsigned* p, unsigned v) { return __hip_atomic_fetch_add(p, v, __ATOMIC_RELAXED, __HIP_MEMORY_SCOPE_AGENT); }
; DI unsigned xb_xcc_id() { return (unsigned)__builtin_amdgcn_s_getreg((3 << 11) | 20) & 0xFu; }
; DI XcdBarrier xcd_barrier_post(unsigned* bar, volatile LAS unsigned* st) {
;   XcdBarrier b; b.bar = bar; b.x = xb_xcc_id(); b.st = st;
;   if (threadIdx.x == 0) (void)xb_add(&bar[XB_XCNT(b.x)], 1u);
;   return b;
; }
; __global__ void __launch_bounds__(NTHREADS, 2) fwd_megakernel(Params p) {
;   extern __shared__ __attribute__((aligned(16))) char smem[];
;   cg::grid_group grid = cg::this_grid();
;   char* ws = p.ws;
;   int toff = 0;
;   __shared__ uint4 xb_words;
;   if (threadIdx.x == 0) xb_words = make_uint4(0u, 0u, 0u, 0u);
;   __syncthreads();
;   const XcdBarrier xb = xcd_barrier_post((unsigned*)(ws + O_BAR), (volatile LAS unsigned*)&xb_words);
_Z14fwd_megakernel6Params:
	s_load_dwordx2 s[88:89], s[0:1], 0xb0
	s_add_u32 s8, s0, 0xb0
	s_addc_u32 s9, s1, 0
	s_mov_b32 s42, s2
	v_mov_b32_e32 v2, 0
	s_waitcnt lgkmcnt(0)
	s_cmp_lt_u32 s2, s88
	s_cselect_b32 s2, 12, 18
	s_add_u32 s2, s8, s2
	s_addc_u32 s3, s9, 0
	global_load_dword v1, v2, s[0:1] offset:190
	global_load_ushort v3, v2, s[2:3]
	s_load_dwordx4 s[84:87], s[0:1], 0xa0
	s_load_dwordx8 s[76:83], s[0:1], 0x80
	v_and_b32_e32 v212, 0x3ff, v0
	v_cmp_eq_u32_e64 s[36:37], 0, v212
	s_waitcnt vmcnt(1)
	v_readfirstlane_b32 s2, v1
	s_nop 1
	v_writelane_b32 v254, s2, 0
	s_waitcnt vmcnt(0)
	v_readfirstlane_b32 s2, v3
	s_nop 1
	v_writelane_b32 v254, s2, 2
	s_and_saveexec_b64 s[4:5], s[36:37]
	v_mov_b32_e32 v3, v2
	v_mov_b32_e32 v4, v2
	v_mov_b32_e32 v5, v2
	ds_write_b128 v2, v[2:5] offset:256
	s_or_b64 exec, exec, s[4:5]
	s_load_dword s2, s[0:1], 0xb8
	s_load_dwordx16 s[44:59], s[0:1], 0x0
	s_waitcnt lgkmcnt(0)
	s_barrier
	v_writelane_b32 v254, s2, 4
	s_add_u32 s92, s86, 0xbfa0000
	s_getreg_b32 s2, hwreg(HW_REG_XCC_ID, 0, 4)
	s_addc_u32 s93, s87, 0
	s_and_b32 s27, s2, 15
	s_and_saveexec_b64 s[4:5], s[36:37]
	s_cbranch_execz .LBB0_5
	s_mov_b64 s[6:7], exec
	v_mbcnt_lo_u32_b32 v1, s6, 0
	v_mbcnt_hi_u32_b32 v1, s7, v1
	v_cmp_eq_u32_e32 vcc, 0, v1
	s_and_b64 s[2:3], exec, vcc
	s_mov_b64 exec, s[2:3]
	s_cbranch_execz .LBB0_5
	s_and_b32 s2, s42, 7
	s_lshl_b32 s2, s2, 2
	s_lshl_b32 s3, 1, s27
	v_mov_b32_e32 v1, s2
	v_mov_b32_e32 v2, s3
	global_atomic_or v2, v1, v2, s[92:93] sc0
	s_waitcnt vmcnt(0)
	s_lshl_b32 s2, s27, 8
	s_bcnt1_i32_b64 s3, s[6:7]
	v_mov_b32_e32 v1, s2
	v_mov_b32_e32 v2, s3
	global_atomic_add v1, v2, s[92:93] offset:1024

; DI unsigned xb_ld(unsigned* p) { return __hip_atomic_load(p, __ATOMIC_RELAXED, __HIP_MEMORY_SCOPE_AGENT); }
; DI void xcd_barrier_complete(unsigned* bar, unsigned x, unsigned& nloc, unsigned& nx) {
;     ...
;     sum = 0u; cnt = 0u; mine = 0u;
; #pragma unroll
;     for (unsigned j = 0; j < 16; ++j) { const unsigned c = xb_ld(&bar[XB_XCNT(j)]); sum += c; cnt += (c > 0u) ? 1u : 0u; mine = (j == x) ? c : mine; }
;     if (sum == G) break;
;     __builtin_amdgcn_s_sleep(1);
;     if ((++sp & 255u) == 0u) { if (xb_ld(&bar[XB_TMO])) break; if (sp > XB_SPIN_CAP) { atomicAdd(&bar[XB_TMO], 1u); break; } }
;   }
;   nloc = mine > 0u ? mine : 1u; nx = cnt > 0u ? cnt : 1u;
; }
; DI void xcd_barrier(const XcdBarrier& b) {
;   asm volatile("s_waitcnt vmcnt(0)" ::: "memory");
;   __syncthreads();
;   if (threadIdx.x == 0) {
;     unsigned* bar = b.bar;
;     __builtin_amdgcn_s_waitcnt(0);
;     unsigned nloc = b.st[0], nx = b.st[1];
;     if (nloc == 0u) { xcd_barrier_complete(bar, b.x, nloc, nx); b.st[0] = nloc; b.st[1] = nx; }
.LBB0_238:
	v_readlane_b32 s2, v254, 5
	s_cmp_eq_u32 s2, 0
	s_cselect_b64 vcc, -1, 0
	s_cmp_eq_u32 s2, 1
	v_cndmask_b32_e32 v1, 0, v17, vcc
	s_cselect_b64 vcc, -1, 0
	s_cmp_eq_u32 s2, 2
	v_cndmask_b32_e32 v1, v1, v2, vcc
	s_cselect_b64 vcc, -1, 0
	s_cmp_eq_u32 s2, 3
	v_cndmask_b32_e32 v1, v1, v3, vcc
	s_cselect_b64 vcc, -1, 0
	s_cmp_eq_u32 s2, 4
	v_cndmask_b32_e32 v1, v1, v4, vcc
	s_cselect_b64 vcc, -1, 0
	s_cmp_eq_u32 s2, 5
	v_cndmask_b32_e32 v1, v1, v5, vcc
	s_cselect_b64 vcc, -1, 0
	s_cmp_eq_u32 s2, 6
	v_cndmask_b32_e32 v1, v1, v6, vcc
	s_cselect_b64 vcc, -1, 0
	s_cmp_eq_u32 s2, 7
	v_cndmask_b32_e32 v1, v1, v7, vcc
	s_cselect_b64 vcc, -1, 0
	s_cmp_eq_u32 s2, 8
	v_cndmask_b32_e32 v1, v1, v8, vcc
	s_cselect_b64 vcc, -1, 0
	s_cmp_eq_u32 s2, 9
	v_cndmask_b32_e32 v1, v1, v9, vcc
	s_cselect_b64 vcc, -1, 0
	s_cmp_eq_u32 s2, 10
	v_cndmask_b32_e32 v1, v1, v10, vcc
	s_cselect_b64 vcc, -1, 0
	s_cmp_eq_u32 s2, 11
	v_cndmask_b32_e32 v1, v1, v11, vcc
	s_cselect_b64 vcc, -1, 0
	s_cmp_eq_u32 s2, 12
	v_cndmask_b32_e32 v1, v1, v12, vcc
	s_cselect_b64 vcc, -1, 0
	s_cmp_eq_u32 s2, 13
	v_cndmask_b32_e32 v1, v1, v13, vcc
	s_cselect_b64 vcc, -1, 0
	s_cmp_eq_u32 s2, 14
	v_cndmask_b32_e32 v1, v1, v14, vcc
	s_cselect_b64 vcc, -1, 0
	s_cmp_eq_u32 s2, 15
	v_cndmask_b32_e32 v1, v1, v15, vcc
	s_cselect_b64 vcc, -1, 0
	v_cndmask_b32_e32 v1, v1, v16, vcc
	v_cmp_ne_u32_e32 vcc, 0, v17
	s_nop 1
	v_cndmask_b32_e64 v17, 0, 1, vcc
	v_cmp_ne_u32_e32 vcc, 0, v2
	s_nop 1
	v_addc_co_u32_e32 v2, vcc, 0, v17, vcc
	v_cmp_ne_u32_e32 vcc, 0, v3
	s_nop 1
	v_cndmask_b32_e64 v3, 0, 1, vcc
	v_cmp_ne_u32_e32 vcc, 0, v4
	s_nop 1
	v_addc_co_u32_e32 v2, vcc, v2, v3, vcc
	v_cmp_ne_u32_e32 vcc, 0, v5
	s_nop 1
	v_cndmask_b32_e64 v3, 0, 1, vcc
	v_cmp_ne_u32_e32 vcc, 0, v6
	s_nop 1
	v_addc_co_u32_e32 v2, vcc, v2, v3, vcc
	v_cmp_ne_u32_e32 vcc, 0, v7
	s_nop 1
	v_cndmask_b32_e64 v3, 0, 1, vcc
	v_cmp_ne_u32_e32 vcc, 0, v8
	s_nop 1
	v_addc_co_u32_e32 v2, vcc, v2, v3, vcc
	v_cmp_ne_u32_e32 vcc, 0, v9
	s_nop 1
	v_cndmask_b32_e64 v3, 0, 1, vcc
	v_cmp_ne_u32_e32 vcc, 0, v10
	s_nop 1
	v_addc_co_u32_e32 v2, vcc, v2, v3, vcc
	v_cmp_ne_u32_e32 vcc, 0, v11
	s_nop 1
	v_cndmask_b32_e64 v3, 0, 1, vcc
	v_cmp_ne_u32_e32 vcc, 0, v12
	s_nop 1
	v_addc_co_u32_e32 v2, vcc, v2, v3, vcc
	v_cmp_ne_u32_e32 vcc, 0, v13
	s_nop 1
	v_cndmask_b32_e64 v3, 0, 1, vcc
	v_cmp_ne_u32_e32 vcc, 0, v14
	s_nop 1
	v_addc_co_u32_e32 v2, vcc, v2, v3, vcc
	v_cmp_ne_u32_e32 vcc, 0, v15
	s_nop 1
	v_cndmask_b32_e64 v3, 0, 1, vcc
	v_cmp_ne_u32_e32 vcc, 0, v16
	s_nop 1
	v_addc_co_u32_e32 v2, vcc, v2, v3, vcc
	v_max_u32_e32 v3, 1, v1
	v_max_u32_e32 v2, 1, v2
	v_mov_b32_e32 v1, 0
	ds_write_b32 v1, v3 offset:256
	ds_write_b32 v1, v2 offset:260
	global_load_dwordx4 v[4:7], v1, s[92:93] sc1
	global_load_dwordx4 v[8:11], v1, s[92:93] offset:16 sc1
	s_waitcnt vmcnt(0)
	v_bcnt_u32_b32 v4, v4, 0
	v_bcnt_u32_b32 v5, v5, 0
	v_bcnt_u32_b32 v6, v6, 0
	v_bcnt_u32_b32 v7, v7, 0
	v_bcnt_u32_b32 v8, v8, 0
	v_bcnt_u32_b32 v9, v9, 0
	v_bcnt_u32_b32 v10, v10, 0
	v_bcnt_u32_b32 v11, v11, 0
	v_max3_u32 v12, v4, v5, v6
	v_max3_u32 v12, v12, v7, v8
	v_max3_u32 v12, v12, v9, v10
	v_max_u32_e32 v12, v12, v11
	v_min3_u32 v13, v4, v5, v6
	v_min3_u32 v13, v13, v7, v8
	v_min3_u32 v13, v13, v9, v10
	v_min_u32_e32 v13, v13, v11
	v_xor_b32_e32 v12, 1, v12
	v_xor_b32_e32 v13, 1, v13
	v_or_b32_e32 v12, v12, v13
	v_cmp_eq_u32_e32 vcc, 0, v12
	s_nop 1
	v_cndmask_b32_e64 v12, 0, 1, vcc
	ds_write_b32 v1, v12 offset:264

; DI unsigned xb_ld(unsigned* p) { return __hip_atomic_load(p, __ATOMIC_RELAXED, __HIP_MEMORY_SCOPE_AGENT); }
; DI unsigned xb_add(unsigned* p, unsigned v) { return __hip_atomic_fetch_add(p, v, __ATOMIC_RELAXED, __HIP_MEMORY_SCOPE_AGENT); }
; #define XB_SPIN(cond, bar) do { unsigned _sp = 0; while (cond) { __builtin_amdgcn_s_sleep(1); \
;     if ((++_sp & 255u) == 0u) { if (xb_ld(&(bar)[XB_TMO])) break; if (_sp > XB_SPIN_CAP) { atomicAdd(&(bar)[XB_TMO], 1u); break; } } } } while (0)
; DI void xcd_barrier(const XcdBarrier& b) {
;     ...
;     const unsigned old = xb_add(&bar[XB_XSUB(b.x)], 1u);
;     const unsigned gen = old / nloc;
;     if (old + 1u == (gen + 1u) * nloc) {
;       __builtin_amdgcn_fence(__ATOMIC_RELEASE, "agent");
;       asm volatile("s_waitcnt vmcnt(0)" ::: "memory");
;       const unsigned og = xb_add(&bar[XB_TOP], 1u);
;       const unsigned tg = og / nx;
;       if (og + 1u == (tg + 1u) * nx) xb_add(&bar[XB_TOPGEN], 1u);
;       else XB_SPIN(xb_ld(&bar[XB_TOPGEN]) == tg, bar);
;       __builtin_amdgcn_fence(__ATOMIC_ACQUIRE, "agent");
;       xb_add(&bar[XB_XGEN(b.x)], 1u);
.LBB0_618:
	s_andn2_saveexec_b64 s[2:3], s[8:9]
	s_cbranch_execz .LBB0_638
	s_mov_b64 s[8:9], exec
	v_mov_b32_e32 v255, 0
	ds_read_b32 v255, v255 offset:264
	s_waitcnt lgkmcnt(0)
	v_cmp_ne_u32_e32 vcc, 0, v255
	s_cbranch_vccnz .LBB0_635
	buffer_wbl2 sc1
	s_waitcnt lgkmcnt(0)
	s_waitcnt vmcnt(0)
	v_mbcnt_lo_u32_b32 v0, s8, 0
	v_mbcnt_hi_u32_b32 v0, s9, v0
	v_cmp_eq_u32_e32 vcc, 0, v0
	s_and_saveexec_b64 s[10:11], vcc
	s_cbranch_execz .LBB0_621
	s_bcnt1_i32_b64 s2, s[8:9]
	v_mov_b32_e32 v2, 0xbfa3000
	v_mov_b32_e32 v3, s2
	global_atomic_add v2, v2, v3, s[86:87] offset:1024 sc0

; DI unsigned xb_ld(unsigned* p) { return __hip_atomic_load(p, __ATOMIC_RELAXED, __HIP_MEMORY_SCOPE_AGENT); }
; DI unsigned xb_add(unsigned* p, unsigned v) { return __hip_atomic_fetch_add(p, v, __ATOMIC_RELAXED, __HIP_MEMORY_SCOPE_AGENT); }
; #define XB_SPIN(cond, bar) do { unsigned _sp = 0; while (cond) { __builtin_amdgcn_s_sleep(1); \
;     if ((++_sp & 255u) == 0u) { if (xb_ld(&(bar)[XB_TMO])) break; if (_sp > XB_SPIN_CAP) { atomicAdd(&(bar)[XB_TMO], 1u); break; } } } } while (0)
; DI void xcd_barrier(const XcdBarrier& b) {
;     ...
;     const unsigned old = xb_add(&bar[XB_XSUB(b.x)], 1u);
;     const unsigned gen = old / nloc;
;     if (old + 1u == (gen + 1u) * nloc) {
;       __builtin_amdgcn_fence(__ATOMIC_RELEASE, "agent");
;       asm volatile("s_waitcnt vmcnt(0)" ::: "memory");
;       const unsigned og = xb_add(&bar[XB_TOP], 1u);
;       const unsigned tg = og / nx;
;       if (og + 1u == (tg + 1u) * nx) xb_add(&bar[XB_TOPGEN], 1u);
;       else XB_SPIN(xb_ld(&bar[XB_TOPGEN]) == tg, bar);
;       __builtin_amdgcn_fence(__ATOMIC_ACQUIRE, "agent");
;       xb_add(&bar[XB_XGEN(b.x)], 1u);
.LBB0_1355:
	s_andn2_saveexec_b64 s[4:5], s[6:7]
	s_cbranch_execz .LBB0_1375
	s_mov_b64 s[6:7], exec
	v_mov_b32_e32 v255, 0
	ds_read_b32 v255, v255 offset:264
	s_waitcnt lgkmcnt(0)
	v_cmp_ne_u32_e32 vcc, 0, v255
	s_cbranch_vccnz .LBB0_1372
	buffer_wbl2 sc1
	s_waitcnt lgkmcnt(0)
	s_waitcnt vmcnt(0)
	v_mbcnt_lo_u32_b32 v0, s6, 0
	v_mbcnt_hi_u32_b32 v0, s7, v0
	v_cmp_eq_u32_e32 vcc, 0, v0
	s_and_saveexec_b64 s[8:9], vcc
	s_cbranch_execz .LBB0_1358
	s_bcnt1_i32_b64 s4, s[6:7]
	v_mov_b32_e32 v2, 0xbfa3000
	v_mov_b32_e32 v3, s4
	global_atomic_add v2, v2, v3, s[86:87] offset:1024 sc0

; __global__ void __launch_bounds__(NTHREADS, 2) fwd_megakernel(Params p) {
;   extern __shared__ __attribute__((aligned(16))) char smem[];
	.amdhsa_kernel _Z14fwd_megakernel6Params
		.amdhsa_group_segment_fixed_size 272
		.amdhsa_private_segment_fixed_size 0
		.amdhsa_kernarg_size 432
		.amdhsa_user_sgpr_count 2
		.amdhsa_user_sgpr_dispatch_ptr 0
		.amdhsa_user_sgpr_queue_ptr 0
		.amdhsa_user_sgpr_kernarg_segment_ptr 1
		.amdhsa_user_sgpr_dispatch_id 0
		.amdhsa_user_sgpr_kernarg_preload_length 0
		.amdhsa_user_sgpr_kernarg_preload_offset 0
		.amdhsa_user_sgpr_private_segment_size 0
		.amdhsa_uses_dynamic_stack 0
		.amdhsa_enable_private_segment 0
		.amdhsa_system_sgpr_workgroup_id_x 1
		.amdhsa_system_sgpr_workgroup_id_y 0
		.amdhsa_system_sgpr_workgroup_id_z 0
		.amdhsa_system_sgpr_workgroup_info 0
		.amdhsa_system_vgpr_workitem_id 2
		.amdhsa_next_free_vgpr 256
		.amdhsa_next_free_sgpr 98
		.amdhsa_accum_offset 256
		.amdhsa_reserve_vcc 1
		.amdhsa_float_round_mode_32 0
		.amdhsa_float_round_mode_16_64 0
		.amdhsa_float_denorm_mode_32 3
		.amdhsa_float_denorm_mode_16_64 3
		.amdhsa_dx10_clamp 1
		.amdhsa_ieee_mode 1
		.amdhsa_fp16_overflow 0
		.amdhsa_tg_split 0
		.amdhsa_exception_fp_ieee_invalid_op 0
		.amdhsa_exception_fp_denorm_src 0
		.amdhsa_exception_fp_ieee_div_zero 0
		.amdhsa_exception_fp_ieee_overflow 0
		.amdhsa_exception_fp_ieee_underflow 0
		.amdhsa_exception_fp_ieee_inexact 0
		.amdhsa_exception_int_div_zero 0
	.end_amdhsa_kernel

; __global__ void __launch_bounds__(NTHREADS, 2) fwd_megakernel(Params p) {
;   extern __shared__ __attribute__((aligned(16))) char smem[];
amdhsa.kernels:
  - .agpr_count:     0
    .args:
      - .offset:         0
        .size:           176
        .value_kind:     by_value
      - .offset:         176
        .size:           4
        .value_kind:     hidden_block_count_x
      - .offset:         180
        .size:           4
        .value_kind:     hidden_block_count_y
      - .offset:         184
        .size:           4
        .value_kind:     hidden_block_count_z
      - .offset:         188
        .size:           2
        .value_kind:     hidden_group_size_x
      - .offset:         190
        .size:           2
        .value_kind:     hidden_group_size_y
      - .offset:         192
        .size:           2
        .value_kind:     hidden_group_size_z
      - .offset:         194
        .size:           2
        .value_kind:     hidden_remainder_x
      - .offset:         196
        .size:           2
        .value_kind:     hidden_remainder_y
      - .offset:         198
        .size:           2
        .value_kind:     hidden_remainder_z
      - .offset:         216
        .size:           8
        .value_kind:     hidden_global_offset_x
      - .offset:         224
        .size:           8
        .value_kind:     hidden_global_offset_y
      - .offset:         232
        .size:           8
        .value_kind:     hidden_global_offset_z
      - .offset:         240
        .size:           2
        .value_kind:     hidden_grid_dims
      - .offset:         264
        .size:           8
        .value_kind:     hidden_multigrid_sync_arg
      - .offset:         296
        .size:           4
        .value_kind:     hidden_dynamic_lds_size
    .group_segment_fixed_size: 272
    .kernarg_segment_align: 8
    .kernarg_segment_size: 432
    .language:       OpenCL C
    .language_version:
      - 2
      - 0
    .max_flat_workgroup_size: 512
    .name:           _Z14fwd_megakernel6Params
    .private_segment_fixed_size: 0
    .sgpr_count:     104
    .sgpr_spill_count: 34
    .symbol:         _Z14fwd_megakernel6Params.kd
    .uniform_work_group_size: 1
    .uses_dynamic_stack: false
    .vgpr_count:     256
    .vgpr_spill_count: 0
    .wavefront_size: 64
